# SSD mixer raw loads de-serialised; SSD item third-segment fragments staged by LDS-DMA (all loads in flight at once); RWKV item second G-record line fetched with the first
# baseline (speedup 1.0000x reference)
.Lsi_third:
	v_lshl_add_u64 v[228:229], v[152:153], 0, v[128:129]
	global_load_dwordx4 v[172:175], v[228:229], off
	global_load_dwordx4 v[176:179], v[228:229], off offset:64
	global_load_dwordx4 v[180:183], v[228:229], off offset:128
	global_load_dwordx4 v[184:187], v[228:229], off offset:192
	v_lshl_add_u64 v[250:251], v[72:73], 0, v[130:131]
	global_load_dwordx4 v[188:191], v[250:251], off
	global_load_dwordx4 v[192:195], v[250:251], off offset:64
	global_load_dwordx4 v[196:199], v[250:251], off offset:128
	global_load_dwordx4 v[200:203], v[250:251], off offset:192
	v_lshl_add_u64 v[254:255], v[152:153], 0, v[130:131]
	global_load_dwordx4 v[204:207], v[254:255], off
	global_load_dwordx4 v[208:211], v[254:255], off offset:64
	global_load_dwordx4 v[212:215], v[254:255], off offset:128
	global_load_dwordx4 v[216:219], v[254:255], off offset:192
	v_lshl_add_u64 v[154:155], v[72:73], 0, v[132:133]
	global_load_dwordx4 v[220:223], v[154:155], off
	global_load_dwordx4 v[224:227], v[154:155], off offset:64
	global_load_dwordx4 v[242:245], v[154:155], off offset:128
	global_load_dwordx4 v[246:249], v[154:155], off offset:192
	s_mul_i32 s98, s97, 0x3000
	s_add_i32 s98, s98, 0x8000
	v_lshl_add_u64 v[228:229], v[152:153], 0, v[132:133]
	s_add_i32 m0, s98, 0
	s_nop 0
	global_load_lds_dwordx4 v[228:229], off
	s_add_i32 m0, s98, 960
	s_nop 0
	global_load_lds_dwordx4 v[228:229], off offset:64
	s_add_i32 m0, s98, 1920
	s_nop 0
	global_load_lds_dwordx4 v[228:229], off offset:128
	s_add_i32 m0, s98, 2880
	s_nop 0
	global_load_lds_dwordx4 v[228:229], off offset:192
	v_lshl_add_u64 v[250:251], v[72:73], 0, v[134:135]
	s_add_i32 m0, s98, 4096
	s_nop 0
	global_load_lds_dwordx4 v[250:251], off
	s_add_i32 m0, s98, 5056
	s_nop 0
	global_load_lds_dwordx4 v[250:251], off offset:64
	s_add_i32 m0, s98, 6016
	s_nop 0
	global_load_lds_dwordx4 v[250:251], off offset:128
	s_add_i32 m0, s98, 6976
	s_nop 0
	global_load_lds_dwordx4 v[250:251], off offset:192
	v_lshl_add_u64 v[254:255], v[152:153], 0, v[134:135]
	s_add_i32 m0, s98, 8192
	s_nop 0
	global_load_lds_dwordx4 v[254:255], off
	s_add_i32 m0, s98, 9152
	s_nop 0
	global_load_lds_dwordx4 v[254:255], off offset:64
	s_add_i32 m0, s98, 10112
	s_nop 0
	global_load_lds_dwordx4 v[254:255], off offset:128
	s_add_i32 m0, s98, 11072
	s_nop 0
	global_load_lds_dwordx4 v[254:255], off offset:192
	v_mbcnt_lo_u32_b32 v228, -1, 0
	v_mbcnt_hi_u32_b32 v228, -1, v228
	v_lshl_add_u32 v228, v228, 4, s98
	s_waitcnt vmcnt(24)
	v_mov_b32_e32 v147, v146
	v_mfma_f32_16x16x32_bf16 v[32:35], v[4:7], v[56:59], 0
	v_mfma_f32_16x16x32_bf16 v[64:67], v[172:175], v[56:59], 0
	v_mfma_f32_16x16x32_bf16 v[32:35], v[12:15], v[60:63], v[32:35]
	v_mfma_f32_16x16x32_bf16 v[64:67], v[176:179], v[60:63], v[64:67]
	v_mfma_f32_16x16x32_bf16 v[32:35], v[20:23], v[52:55], v[32:35]
	v_mfma_f32_16x16x32_bf16 v[64:67], v[180:183], v[52:55], v[64:67]
	v_mfma_f32_16x16x32_bf16 v[32:35], v[16:19], v[8:11], v[32:35]
	v_mfma_f32_16x16x32_bf16 v[64:67], v[184:187], v[8:11], v[64:67]
	v_mfma_f32_16x16x32_bf16 v[76:79], v[4:7], v[48:51], 0
	v_mfma_f32_16x16x32_bf16 v[68:71], v[172:175], v[48:51], 0
	v_mfma_f32_16x16x32_bf16 v[76:79], v[12:15], v[44:47], v[76:79]
	v_mfma_f32_16x16x32_bf16 v[68:71], v[176:179], v[44:47], v[68:71]
	v_mfma_f32_16x16x32_bf16 v[76:79], v[20:23], v[40:43], v[76:79]
	v_mfma_f32_16x16x32_bf16 v[68:71], v[180:183], v[40:43], v[68:71]
	v_mfma_f32_16x16x32_bf16 v[16:19], v[16:19], v[36:39], v[76:79]
	v_mfma_f32_16x16x32_bf16 v[68:71], v[184:187], v[36:39], v[68:71]
	s_nop 7
	s_and_b64 vcc, exec, s[30:31]
	s_cbranch_vccz .Lsi_c0
	v_pk_fma_f32 v[32:33], v[146:147], v[32:33], v[64:65]
	v_pk_fma_f32 v[34:35], v[146:147], v[34:35], v[66:67]
.Lsi_c0:
	v_pk_fma_f32 v[16:17], v[146:147], v[16:17], v[68:69]
	v_pk_fma_f32 v[18:19], v[146:147], v[18:19], v[70:71]
	s_waitcnt vmcnt(16)
	v_mfma_f32_16x16x32_bf16 v[28:31], v[188:191], v[56:59], 0
	v_mfma_f32_16x16x32_bf16 v[64:67], v[204:207], v[56:59], 0
	v_mfma_f32_16x16x32_bf16 v[28:31], v[192:195], v[60:63], v[28:31]
	v_mfma_f32_16x16x32_bf16 v[64:67], v[208:211], v[60:63], v[64:67]
	v_mfma_f32_16x16x32_bf16 v[28:31], v[196:199], v[52:55], v[28:31]
	v_mfma_f32_16x16x32_bf16 v[64:67], v[212:215], v[52:55], v[64:67]
	v_mfma_f32_16x16x32_bf16 v[28:31], v[200:203], v[8:11], v[28:31]
	v_mfma_f32_16x16x32_bf16 v[64:67], v[216:219], v[8:11], v[64:67]
	v_mfma_f32_16x16x32_bf16 v[76:79], v[188:191], v[48:51], 0
	v_mfma_f32_16x16x32_bf16 v[68:71], v[204:207], v[48:51], 0
	v_mfma_f32_16x16x32_bf16 v[76:79], v[192:195], v[44:47], v[76:79]
	v_mfma_f32_16x16x32_bf16 v[68:71], v[208:211], v[44:47], v[68:71]
	v_mfma_f32_16x16x32_bf16 v[76:79], v[196:199], v[40:43], v[76:79]
	v_mfma_f32_16x16x32_bf16 v[68:71], v[212:215], v[40:43], v[68:71]
	v_mfma_f32_16x16x32_bf16 v[12:15], v[200:203], v[36:39], v[76:79]
	v_mfma_f32_16x16x32_bf16 v[68:71], v[216:219], v[36:39], v[68:71]
	s_nop 7
	s_and_b64 vcc, exec, s[30:31]
	s_cbranch_vccz .Lsi_c1
	v_pk_fma_f32 v[28:29], v[146:147], v[28:29], v[64:65]
	v_pk_fma_f32 v[30:31], v[146:147], v[30:31], v[66:67]
.Lsi_c1:
	v_pk_fma_f32 v[12:13], v[146:147], v[12:13], v[68:69]
	v_pk_fma_f32 v[14:15], v[146:147], v[14:15], v[70:71]
	s_waitcnt vmcnt(8)
	ds_read_b128 v[172:175], v228
	ds_read_b128 v[176:179], v228 offset:1024
	ds_read_b128 v[180:183], v228 offset:2048
	ds_read_b128 v[184:187], v228 offset:3072
	s_waitcnt lgkmcnt(0)
	v_mfma_f32_16x16x32_bf16 v[24:27], v[220:223], v[56:59], 0
	v_mfma_f32_16x16x32_bf16 v[64:67], v[172:175], v[56:59], 0
	v_mfma_f32_16x16x32_bf16 v[24:27], v[224:227], v[60:63], v[24:27]
	v_mfma_f32_16x16x32_bf16 v[64:67], v[176:179], v[60:63], v[64:67]
	v_mfma_f32_16x16x32_bf16 v[24:27], v[242:245], v[52:55], v[24:27]
	v_mfma_f32_16x16x32_bf16 v[64:67], v[180:183], v[52:55], v[64:67]
	v_mfma_f32_16x16x32_bf16 v[24:27], v[246:249], v[8:11], v[24:27]
	v_mfma_f32_16x16x32_bf16 v[64:67], v[184:187], v[8:11], v[64:67]
	v_mfma_f32_16x16x32_bf16 v[76:79], v[220:223], v[48:51], 0
	v_mfma_f32_16x16x32_bf16 v[68:71], v[172:175], v[48:51], 0
	v_mfma_f32_16x16x32_bf16 v[76:79], v[224:227], v[44:47], v[76:79]
	v_mfma_f32_16x16x32_bf16 v[68:71], v[176:179], v[44:47], v[68:71]
	v_mfma_f32_16x16x32_bf16 v[76:79], v[242:245], v[40:43], v[76:79]
	v_mfma_f32_16x16x32_bf16 v[68:71], v[180:183], v[40:43], v[68:71]
	v_mfma_f32_16x16x32_bf16 v[4:7], v[246:249], v[36:39], v[76:79]
	v_mfma_f32_16x16x32_bf16 v[68:71], v[184:187], v[36:39], v[68:71]
	s_nop 7
	s_and_b64 vcc, exec, s[30:31]
	s_cbranch_vccz .Lsi_c2
	v_pk_fma_f32 v[24:25], v[146:147], v[24:25], v[64:65]
	v_pk_fma_f32 v[26:27], v[146:147], v[26:27], v[66:67]
.Lsi_c2:
	v_pk_fma_f32 v[4:5], v[146:147], v[4:5], v[68:69]
	v_pk_fma_f32 v[6:7], v[146:147], v[6:7], v[70:71]
	s_waitcnt vmcnt(0)
	ds_read_b128 v[188:191], v228 offset:4096
	ds_read_b128 v[192:195], v228 offset:5120
	ds_read_b128 v[196:199], v228 offset:6144
	ds_read_b128 v[200:203], v228 offset:7168
	ds_read_b128 v[204:207], v228 offset:8192
	ds_read_b128 v[208:211], v228 offset:9216
	ds_read_b128 v[212:215], v228 offset:10240
	ds_read_b128 v[216:219], v228 offset:11264
	s_waitcnt lgkmcnt(0)
	v_mfma_f32_16x16x32_bf16 v[20:23], v[188:191], v[56:59], 0
	v_mfma_f32_16x16x32_bf16 v[64:67], v[204:207], v[56:59], 0
	v_mfma_f32_16x16x32_bf16 v[20:23], v[192:195], v[60:63], v[20:23]
	v_mfma_f32_16x16x32_bf16 v[64:67], v[208:211], v[60:63], v[64:67]
	v_mfma_f32_16x16x32_bf16 v[20:23], v[196:199], v[52:55], v[20:23]
	v_mfma_f32_16x16x32_bf16 v[64:67], v[212:215], v[52:55], v[64:67]
	v_mfma_f32_16x16x32_bf16 v[20:23], v[200:203], v[8:11], v[20:23]
	v_mfma_f32_16x16x32_bf16 v[64:67], v[216:219], v[8:11], v[64:67]
	v_mfma_f32_16x16x32_bf16 v[76:79], v[188:191], v[48:51], 0
	v_mfma_f32_16x16x32_bf16 v[68:71], v[204:207], v[48:51], 0
	v_mfma_f32_16x16x32_bf16 v[76:79], v[192:195], v[44:47], v[76:79]
	v_mfma_f32_16x16x32_bf16 v[68:71], v[208:211], v[44:47], v[68:71]
	v_mfma_f32_16x16x32_bf16 v[76:79], v[196:199], v[40:43], v[76:79]
	v_mfma_f32_16x16x32_bf16 v[68:71], v[212:215], v[40:43], v[68:71]
	v_mfma_f32_16x16x32_bf16 v[8:11], v[200:203], v[36:39], v[76:79]
	v_mfma_f32_16x16x32_bf16 v[68:71], v[216:219], v[36:39], v[68:71]
	s_nop 7
	s_and_b64 vcc, exec, s[30:31]
	s_cbranch_vccz .Lsi_c3
	v_pk_fma_f32 v[20:21], v[146:147], v[20:21], v[64:65]
	v_pk_fma_f32 v[22:23], v[146:147], v[22:23], v[66:67]

.LBB0_1009:
	s_ashr_i32 s21, s20, 31
	s_mul_i32 s7, s20, 0x1100000
	s_mul_hi_i32 s6, s20, 0x1100000
	s_add_u32 s26, s38, s7
	s_addc_u32 s27, s39, s6
	s_lshl_b64 s[6:7], s[20:21], 22
	s_add_u32 s6, s0, s6
	s_addc_u32 s7, s1, s7
	s_ashr_i32 s25, s24, 31
	s_lshl_b64 s[28:29], s[24:25], 13
	s_add_u32 s4, s40, s4
	s_addc_u32 s5, s41, s5
	s_mul_i32 s25, s22, 0x4100
	s_mul_hi_i32 s21, s22, 0x4100
	s_add_u32 s4, s4, s25
	s_addc_u32 s5, s5, s21
	v_lshlrev_b32_e32 v2, 2, v0
	v_lshl_add_u64 v[4:5], s[4:5], 0, v[2:3]
	v_add_co_u32_e32 v6, vcc, s65, v4
	v_lshlrev_b32_e32 v2, 1, v110
	s_nop 0
	v_addc_co_u32_e32 v7, vcc, 0, v5, vcc
	global_load_dword v168, v[6:7], off
	v_lshlrev_b32_e32 v6, 1, v106
	v_mov_b32_e32 v7, v3
	v_lshl_add_u64 v[8:9], s[4:5], 0, v[2:3]
	v_lshl_add_u64 v[6:7], v[8:9], 0, v[6:7]
	v_add_co_u32_e32 v12, vcc, s63, v6
	s_mov_b64 s[4:5], 0x2000
	s_nop 0
	v_addc_co_u32_e32 v13, vcc, 0, v7, vcc
	v_lshlrev_b32_e32 v2, 1, v112
	v_add_co_u32_e32 v4, vcc, s58, v4
	v_lshl_add_u64 v[10:11], v[6:7], 0, s[4:5]
	global_load_dwordx4 v[24:27], v[12:13], off
	global_load_dwordx4 v[20:23], v[10:11], off offset:64
	v_lshl_add_u64 v[12:13], v[8:9], 0, v[2:3]
	v_addc_co_u32_e32 v5, vcc, 0, v5, vcc
	s_mov_b64 s[4:5], 0x6100
	global_load_dwordx2 v[36:37], v[12:13], off
	global_load_dwordx2 v[48:49], v[12:13], off offset:32
	global_load_dwordx2 v[68:69], v[12:13], off offset:64
	global_load_dwordx2 v[58:59], v[12:13], off offset:96
	global_load_dword v2, v[4:5], off offset:256
	v_lshl_add_u64 v[4:5], v[6:7], 0, s[4:5]
	v_add_co_u32_e32 v6, vcc, s57, v6
	s_mov_b64 s[4:5], 0x4100
	s_nop 0
	v_addc_co_u32_e32 v7, vcc, 0, v7, vcc
	v_lshl_add_u64 v[14:15], v[12:13], 0, s[4:5]
	v_add_co_u32_e32 v12, vcc, s65, v12
	global_load_dwordx4 v[8:11], v[6:7], off offset:256
	s_nop 0
	global_load_dwordx4 v[4:7], v[4:5], off offset:64
	v_addc_co_u32_e32 v13, vcc, 0, v13, vcc
	global_load_dwordx2 v[184:185], v[12:13], off offset:256
	global_load_dwordx2 v[182:183], v[14:15], off offset:32
	global_load_dwordx2 v[180:181], v[14:15], off offset:64
	global_load_dwordx2 v[178:179], v[14:15], off offset:96
	v_lshl_add_u64 v[12:13], v[118:119], 0, s[28:29]
	s_mov_b64 s[4:5], 0x80000
	v_lshl_add_u64 v[14:15], v[12:13], 0, s[4:5]
	s_mov_b32 s4, 0x81000
	v_add_co_u32_e32 v12, vcc, s4, v12
	s_lshl_b32 s4, s55, 6
	s_nop 0
	v_addc_co_u32_e32 v13, vcc, 0, v13, vcc
	global_load_dwordx4 v[64:67], v[12:13], off offset:-4096
	global_load_dwordx4 v[60:63], v[14:15], off offset:64
	global_load_dwordx4 v[44:47], v[14:15], off offset:2048
	global_load_dwordx4 v[40:43], v[14:15], off offset:2112
	global_load_dwordx4 v[32:35], v[12:13], off
	global_load_dwordx4 v[28:31], v[12:13], off offset:64
	global_load_dwordx4 v[16:19], v[12:13], off offset:2048
	s_nop 0
	global_load_dwordx4 v[12:15], v[12:13], off offset:2112
	v_or_b32_e32 v78, s4, v112
	s_lshl_b32 s5, s54, 6
	v_or_b32_e32 v76, s5, v0
	v_mov_b64_e32 v[38:39], s[26:27]
	v_add_u32_e32 v74, 16, v78
	v_or_b32_e32 v86, 32, v78
	v_ashrrev_i32_e32 v79, 31, v78
	v_mad_i64_i32 v[50:51], s[26:27], v76, s64, v[38:39]
	s_mov_b64 s[28:29], 0x1600
	v_add_u32_e32 v52, -1, v76
	v_ashrrev_i32_e32 v75, 31, v74
	v_ashrrev_i32_e32 v87, 31, v86
	v_lshl_add_u64 v[70:71], v[50:51], 0, s[72:73]
	v_lshl_add_u64 v[50:51], v[50:51], 0, s[28:29]
	v_mad_i64_i32 v[52:53], s[26:27], v52, s64, v[38:39]
	v_lshlrev_b64 v[148:149], 1, v[78:79]
	v_lshlrev_b64 v[74:75], 1, v[74:75]
	v_lshlrev_b64 v[86:87], 1, v[86:87]
	v_lshl_add_u64 v[72:73], v[52:53], 0, s[28:29]
	v_lshl_add_u64 v[54:55], v[50:51], 0, v[148:149]
	v_lshl_add_u64 v[80:81], v[70:71], 0, v[74:75]
	v_lshl_add_u64 v[88:89], v[70:71], 0, v[86:87]
	global_load_dwordx2 v[54:55], v[54:55], off
	v_lshl_add_u64 v[84:85], v[72:73], 0, v[74:75]
	global_load_dwordx2 v[80:81], v[80:81], off
	v_lshl_add_u64 v[52:53], v[70:71], 0, v[148:149]
	global_load_dwordx2 v[90:91], v[88:89], off
	v_lshl_add_u64 v[88:89], v[50:51], 0, v[86:87]
	global_load_dwordx2 v[84:85], v[84:85], off
	v_lshl_add_u64 v[82:83], v[50:51], 0, v[74:75]
	global_load_dwordx2 v[92:93], v[88:89], off
	v_lshl_add_u64 v[88:89], v[72:73], 0, v[86:87]
	global_load_dwordx2 v[94:95], v[88:89], off
	v_add_u32_e32 v88, 48, v78
	v_ashrrev_i32_e32 v89, 31, v88
	v_lshlrev_b64 v[88:89], 1, v[88:89]
	v_lshl_add_u64 v[70:71], v[70:71], 0, v[88:89]
	v_lshl_add_u64 v[50:51], v[50:51], 0, v[88:89]
	global_load_dwordx2 v[52:53], v[52:53], off
	v_add_u32_e32 v176, s5, v1
	global_load_dwordx2 v[82:83], v[82:83], off
	v_lshl_add_u64 v[56:57], v[72:73], 0, v[148:149]
	global_load_dwordx2 v[190:191], v[70:71], off
	global_load_dwordx2 v[192:193], v[50:51], off
	v_lshl_add_u64 v[50:51], v[72:73], 0, v[88:89]
	global_load_dwordx2 v[194:195], v[50:51], off
	v_mad_i64_i32 v[50:51], s[26:27], v176, s64, v[38:39]
	v_lshl_add_u64 v[70:71], v[50:51], 0, s[72:73]
	v_add_u32_e32 v72, -1, v176
	v_lshl_add_u64 v[50:51], v[50:51], 0, s[28:29]
	v_mad_i64_i32 v[38:39], s[26:27], v72, s64, v[38:39]
	v_lshl_add_u64 v[72:73], v[70:71], 0, v[148:149]
	v_lshl_add_u64 v[38:39], v[38:39], 0, s[28:29]
	global_load_dwordx2 v[172:173], v[72:73], off
	v_lshl_add_u64 v[72:73], v[50:51], 0, v[148:149]
	global_load_dwordx2 v[170:171], v[72:73], off
	v_lshl_add_u64 v[72:73], v[38:39], 0, v[148:149]
	global_load_dwordx2 v[174:175], v[72:73], off
	v_lshl_add_u64 v[72:73], v[70:71], 0, v[74:75]
	global_load_dwordx2 v[150:151], v[72:73], off
	v_lshl_add_u64 v[72:73], v[50:51], 0, v[74:75]
	global_load_dwordx2 v[152:153], v[72:73], off
	v_lshl_add_u64 v[72:73], v[38:39], 0, v[74:75]
	global_load_dwordx2 v[154:155], v[72:73], off
	v_lshl_add_u64 v[72:73], v[70:71], 0, v[86:87]
	global_load_dwordx2 v[142:143], v[72:73], off
	v_lshl_add_u64 v[72:73], v[50:51], 0, v[86:87]
	global_load_dwordx2 v[144:145], v[72:73], off
	v_lshl_add_u64 v[72:73], v[38:39], 0, v[86:87]
	v_lshl_add_u64 v[70:71], v[70:71], 0, v[88:89]
	v_lshl_add_u64 v[50:51], v[50:51], 0, v[88:89]
	v_lshl_add_u64 v[38:39], v[38:39], 0, v[88:89]
	global_load_dwordx2 v[56:57], v[56:57], off
	s_waitcnt vmcnt(35)
	v_lshlrev_b32_e32 v74, 16, v59
	global_load_dwordx2 v[136:137], v[70:71], off
	global_load_dwordx2 v[138:139], v[50:51], off
	global_load_dwordx2 v[140:141], v[38:39], off
	v_and_b32_e32 v39, 64, v234
	v_xor_b32_e32 v38, 16, v234
	v_add_u32_e32 v39, 64, v39
	v_cmp_lt_i32_e32 vcc, v38, v39
	global_load_dwordx2 v[146:147], v[72:73], off
	v_lshlrev_b32_e32 v70, 16, v36
	v_cndmask_b32_e32 v38, v234, v38, vcc
	v_lshlrev_b32_e32 v131, 2, v38
	v_xor_b32_e32 v38, 32, v234
	v_cmp_lt_i32_e32 vcc, v38, v39
	v_and_b32_e32 v71, 0xffff0000, v36
	v_lshlrev_b32_e32 v72, 16, v37
	v_cndmask_b32_e32 v38, v234, v38, vcc
	v_and_b32_e32 v73, 0xffff0000, v37
	v_lshlrev_b32_e32 v129, 2, v38
	v_and_b32_e32 v75, 0xffff0000, v59
	s_waitcnt vmcnt(31)
	v_mfma_f32_16x16x32_bf16 v[36:39], v[64:67], v[24:27], v[70:73]
	s_ashr_i32 s5, s4, 31
	v_ashrrev_i32_e32 v77, 31, v76
	v_lshl_add_u64 v[102:103], s[4:5], 2, v[126:127]
	s_waitcnt vmcnt(30)
	v_mfma_f32_16x16x32_bf16 v[36:39], v[60:63], v[20:23], v[36:39]
	v_lshlrev_b32_e32 v72, 16, v49
	v_and_b32_e32 v73, 0xffff0000, v49
	v_ashrrev_i32_e32 v177, 31, v176
	s_waitcnt vmcnt(22)
	v_lshlrev_b32_e32 v100, 16, v80
	v_and_b32_e32 v101, 0xffff0000, v80
	s_nop 1
	v_mov_b32_e32 v50, v37
	v_mov_b32_e32 v51, v38
	v_mov_b32_e32 v70, v36
	v_mov_b32_e32 v71, v39
	v_pk_add_f32 v[50:51], v[50:51], v[70:71]
	v_lshlrev_b32_e32 v70, 16, v48
	v_add_f32_e32 v50, v50, v51
	v_and_b32_e32 v71, 0xffff0000, v48
	v_add_f32_e32 v86, 0, v50
	v_mul_f32_e32 v80, 0xbfb8aa3b, v100
	v_mfma_f32_16x16x32_bf16 v[48:51], v[44:47], v[24:27], v[70:73]
	v_exp_f32_e32 v80, v80
	s_waitcnt vmcnt(17)
	v_and_b32_e32 v59, 0xffff0000, v52
	v_lshlrev_b32_e32 v208, 16, v84
	v_mfma_f32_16x16x32_bf16 v[48:51], v[40:43], v[20:23], v[48:51]
	v_add_f32_e32 v80, 1.0, v80
	v_rcp_f32_e32 v212, v80
	v_mul_f32_e32 v80, 0xbfb8aa3b, v101
	v_exp_f32_e32 v80, v80
	s_waitcnt vmcnt(16)
	v_lshlrev_b32_e32 v196, 16, v82
	s_nop 1
	v_mov_b32_e32 v70, v49
	v_mov_b32_e32 v71, v50
	v_mov_b32_e32 v72, v48
	v_mov_b32_e32 v73, v51
	v_pk_add_f32 v[70:71], v[70:71], v[72:73]
	v_lshlrev_b32_e32 v72, 16, v69
	v_pk_add_f32 v[88:89], v[70:71], v[70:71] op_sel:[0,1] op_sel_hi:[1,0]
	v_lshlrev_b32_e32 v70, 16, v68
	v_and_b32_e32 v71, 0xffff0000, v68
	v_and_b32_e32 v73, 0xffff0000, v69
	v_add_f32_e32 v80, 1.0, v80
	v_rcp_f32_e32 v213, v80
	v_mfma_f32_16x16x32_bf16 v[68:71], v[32:35], v[24:27], v[70:73]
	v_and_b32_e32 v197, 0xffff0000, v82
	v_and_b32_e32 v209, 0xffff0000, v84
	v_lshlrev_b32_e32 v82, 16, v83
	v_lshlrev_b32_e32 v72, 16, v58
	v_and_b32_e32 v73, 0xffff0000, v58
	v_mfma_f32_16x16x32_bf16 v[68:71], v[28:31], v[20:23], v[68:71]
	v_and_b32_e32 v83, 0xffff0000, v83
	v_lshlrev_b32_e32 v84, 16, v85
	v_and_b32_e32 v85, 0xffff0000, v85
	v_mfma_f32_16x16x32_bf16 v[24:27], v[16:19], v[24:27], v[72:75]
	v_lshlrev_b32_e32 v80, 16, v81
	s_nop 2
	v_add_f32_e32 v96, v68, v69
	v_add_f32_e32 v98, v70, v71
	v_mfma_f32_16x16x32_bf16 v[72:75], v[12:15], v[20:23], v[24:27]
	v_and_b32_e32 v81, 0xffff0000, v81
	v_pk_add_f32 v[84:85], v[84:85], v[82:83] neg_lo:[0,1] neg_hi:[0,1]
	v_pk_mul_f32 v[212:213], v[212:213], v[100:101]
	v_mul_f32_e32 v100, 0xbfb8aa3b, v80
	v_exp_f32_e32 v100, v100
	s_nop 2
	v_mov_b32_e32 v87, v72
	v_mov_b32_e32 v89, v73
	v_mov_b32_e32 v97, v74
	v_mov_b32_e32 v99, v75
	v_pk_add_f32 v[20:21], v[86:87], v[88:89]
	v_pk_add_f32 v[22:23], v[96:97], v[98:99]
	v_lshlrev_b32_e32 v86, 16, v54
	v_pk_add_f32 v[20:21], v[20:21], v[22:23]
	v_and_b32_e32 v87, 0xffff0000, v54
	v_add_f32_e32 v20, v20, v21
	ds_bpermute_b32 v21, v131, v20
	s_waitcnt vmcnt(4)
	v_lshlrev_b32_e32 v88, 16, v56
	v_and_b32_e32 v89, 0xffff0000, v56
	v_lshlrev_b32_e32 v54, 16, v55
	v_and_b32_e32 v55, 0xffff0000, v55
	s_waitcnt lgkmcnt(0)
	v_add_f32_e32 v20, v20, v21
	ds_bpermute_b32 v21, v129, v20
	v_lshlrev_b32_e32 v56, 16, v57
	v_and_b32_e32 v57, 0xffff0000, v57
	v_pk_add_f32 v[56:57], v[56:57], v[54:55] neg_lo:[0,1] neg_hi:[0,1]
	v_pk_add_f32 v[88:89], v[88:89], v[86:87] neg_lo:[0,1] neg_hi:[0,1]
	s_waitcnt lgkmcnt(0)
	v_add_f32_e32 v58, v20, v21
	v_fmamk_f32 v189, v58, 0xbc800000, v37
	v_fmamk_f32 v188, v58, 0xbc800000, v36
	v_fmamk_f32 v39, v58, 0xbc800000, v39
	v_fmac_f32_e32 v38, 0xbc800000, v58
	v_pk_mul_f32 v[20:21], v[38:39], v[38:39]
	v_pk_mul_f32 v[22:23], v[188:189], v[188:189]
	v_fmamk_f32 v187, v58, 0xbc800000, v49
	v_pk_mov_b32 v[24:25], v[22:23], v[20:21] op_sel:[1,0]
	v_mov_b32_e32 v23, v21
	v_pk_add_f32 v[20:21], v[24:25], v[22:23]
	v_fmamk_f32 v186, v58, 0xbc800000, v48
	v_fmamk_f32 v51, v58, 0xbc800000, v51
	v_fmac_f32_e32 v50, 0xbc800000, v58
	v_pk_add_f32 v[20:21], v[20:21], v[20:21] op_sel_hi:[0,1]
	v_pk_mul_f32 v[22:23], v[50:51], v[50:51]
	v_pk_mul_f32 v[24:25], v[186:187], v[186:187]
	v_fmac_f32_e32 v68, 0xbc800000, v58
	v_pk_mov_b32 v[26:27], v[24:25], v[22:23] op_sel:[1,0]
	v_mov_b32_e32 v25, v23
	v_fmamk_f32 v48, v58, 0xbc800000, v70
	v_fmamk_f32 v69, v58, 0xbc800000, v69
	v_mul_f32_e32 v20, v68, v68
	v_pk_add_f32 v[22:23], v[26:27], v[24:25]
	v_fmamk_f32 v49, v58, 0xbc800000, v71
	v_pk_fma_f32 v[24:25], v[68:69], v[68:69], v[20:21] op_sel_hi:[1,1,0]
	v_mul_f32_e32 v20, v48, v48
	v_pk_add_f32 v[22:23], v[22:23], v[22:23] op_sel_hi:[0,1]
	v_pk_fma_f32 v[26:27], v[48:49], v[48:49], v[20:21] op_sel_hi:[1,1,0]
	v_fmamk_f32 v37, v58, 0xbc800000, v75
	v_fmamk_f32 v36, v58, 0xbc800000, v74
	v_fmamk_f32 v73, v58, 0xbc800000, v73
	v_fmac_f32_e32 v72, 0xbc800000, v58
	v_mul_f32_e32 v24, v72, v72
	v_mul_f32_e32 v26, v73, v73
	v_mul_f32_e32 v20, v36, v36
	v_mul_f32_e32 v22, v37, v37
	v_pk_add_f32 v[24:25], v[24:25], v[26:27]
	v_pk_add_f32 v[20:21], v[20:21], v[22:23]
	v_lshlrev_b32_e32 v58, 16, v52
	v_pk_add_f32 v[70:71], v[24:25], v[20:21]
	v_lshlrev_b64 v[20:21], 11, v[76:77]
	global_load_dwordx4 v[74:77], v[102:103], off offset:2048
	global_load_dwordx4 v[246:249], v[102:103], off offset:2176
	global_load_dwordx2 v[250:251], v[102:103], off offset:2240
	global_load_dwordx2 v[254:255], v[102:103], off offset:2248
	v_mul_f32_e32 v52, 0xbfb8aa3b, v58
	v_exp_f32_e32 v52, v52
	v_lshlrev_b64 v[24:25], 2, v[78:79]
	v_mov_b32_e32 v79, s5
	v_lshl_add_u64 v[98:99], s[6:7], 0, v[20:21]
	v_add_f32_e32 v52, 1.0, v52
	v_rcp_f32_e32 v96, v52
	v_mul_f32_e32 v52, 0xbfb8aa3b, v59
	v_exp_f32_e32 v52, v52
	v_lshl_add_u64 v[20:21], s[8:9], 0, v[24:25]
	v_lshl_add_u64 v[24:25], s[10:11], 0, v[24:25]
	global_load_dwordx4 v[20:23], v[20:21], off
	v_add_f32_e32 v52, 1.0, v52
	v_rcp_f32_e32 v97, v52
	v_lshlrev_b32_e32 v52, 16, v53
	v_and_b32_e32 v53, 0xffff0000, v53
	global_load_dwordx4 v[24:27], v[24:25], off
	v_pk_mul_f32 v[200:201], v[96:97], v[58:59]
	v_mul_f32_e32 v58, 0xbfb8aa3b, v52
	v_exp_f32_e32 v58, v58
	v_add_f32_e32 v100, 1.0, v100
	v_rcp_f32_e32 v100, v100
	v_pk_add_f32 v[208:209], v[208:209], v[196:197] neg_lo:[0,1] neg_hi:[0,1]
	v_add_f32_e32 v58, 1.0, v58
	v_rcp_f32_e32 v58, v58
	v_lshl_add_u64 v[204:205], v[98:99], 0, v[148:149]
	v_lshlrev_b32_e32 v220, 16, v90
	v_and_b32_e32 v221, 0xffff0000, v90
	v_mul_f32_e32 v90, 0xbfb8aa3b, v220
	v_exp_f32_e32 v90, v90
	v_lshlrev_b32_e32 v218, 16, v92
	v_and_b32_e32 v219, 0xffff0000, v92
	v_lshlrev_b32_e32 v222, 16, v94
	v_add_f32_e32 v90, 1.0, v90
	v_rcp_f32_e32 v224, v90
	v_mul_f32_e32 v90, 0xbfb8aa3b, v221
	v_exp_f32_e32 v90, v90
	v_and_b32_e32 v223, 0xffff0000, v94
	v_lshlrev_b32_e32 v92, 16, v93
	v_and_b32_e32 v93, 0xffff0000, v93
	v_add_f32_e32 v90, 1.0, v90
	v_lshlrev_b32_e32 v94, 16, v95
	v_and_b32_e32 v95, 0xffff0000, v95
	v_pk_add_f32 v[222:223], v[222:223], v[218:219] neg_lo:[0,1] neg_hi:[0,1]
	v_rcp_f32_e32 v225, v90
	v_lshlrev_b32_e32 v90, 16, v91
	v_and_b32_e32 v91, 0xffff0000, v91
	v_pk_add_f32 v[94:95], v[94:95], v[92:93] neg_lo:[0,1] neg_hi:[0,1]
	v_mul_f32_e32 v133, 0xbfb8aa3b, v90
	v_exp_f32_e32 v133, v133
	v_pk_mul_f32 v[220:221], v[224:225], v[220:221]
	v_lshlrev_b32_e32 v228, 16, v190
	v_and_b32_e32 v229, 0xffff0000, v190
	v_add_f32_e32 v133, 1.0, v133
	v_rcp_f32_e32 v224, v133
	v_mul_f32_e32 v133, 0xbfb8aa3b, v228
	v_exp_f32_e32 v133, v133
	v_lshlrev_b32_e32 v226, 16, v192
	v_and_b32_e32 v227, 0xffff0000, v192
	v_lshlrev_b32_e32 v242, 16, v194
	v_add_f32_e32 v133, 1.0, v133
	v_rcp_f32_e32 v244, v133
	v_mul_f32_e32 v133, 0xbfb8aa3b, v229
	v_exp_f32_e32 v133, v133
	v_and_b32_e32 v243, 0xffff0000, v194
	v_pk_add_f32 v[242:243], v[242:243], v[226:227] neg_lo:[0,1] neg_hi:[0,1]
	v_lshlrev_b32_e32 v190, 16, v193
	v_add_f32_e32 v133, 1.0, v133
	v_rcp_f32_e32 v245, v133
	v_lshlrev_b32_e32 v192, 16, v195
	v_pk_mul_f32 v[228:229], v[244:245], v[228:229]
	v_lshlrev_b32_e32 v244, 16, v185
	v_and_b32_e32 v245, 0xffff0000, v185
	s_waitcnt vmcnt(2)
	v_pk_fma_f32 v[202:203], v[56:57], v[76:77], v[54:55]
	v_mul_f32_e32 v54, 0xbfb8aa3b, v53
	v_exp_f32_e32 v54, v54
	v_lshlrev_b64 v[56:57], 2, v[78:79]
	v_lshl_add_u64 v[96:97], s[8:9], 0, v[56:57]
	v_lshl_add_u64 v[104:105], s[10:11], 0, v[56:57]
	v_add_f32_e32 v54, 1.0, v54
	v_rcp_f32_e32 v59, v54
	v_pk_fma_f32 v[198:199], v[88:89], v[74:75], v[86:87]
	v_pk_mul_f32 v[206:207], v[58:59], v[52:53]
	global_load_dwordx4 v[52:55], v[96:97], off offset:64
	global_load_dwordx4 v[56:59], v[104:105], off offset:64
	global_load_dwordx4 v[86:89], v[102:103], off offset:2112
	s_waitcnt vmcnt(0)
	v_pk_fma_f32 v[214:215], v[84:85], v[88:89], v[82:83]
	v_mul_f32_e32 v82, 0xbfb8aa3b, v81
	v_exp_f32_e32 v82, v82
	v_pk_fma_f32 v[210:211], v[208:209], v[86:87], v[196:197]
	v_lshlrev_b64 v[196:197], 1, v[78:79]
	v_lshl_add_u64 v[208:209], v[98:99], 0, v[196:197]
	v_add_f32_e32 v82, 1.0, v82
	v_rcp_f32_e32 v101, v82
	s_nop 0
	v_pk_mul_f32 v[216:217], v[100:101], v[80:81]
	global_load_dwordx4 v[78:81], v[96:97], off offset:128
	global_load_dwordx4 v[82:85], v[104:105], off offset:128
	v_mov_b64_e32 v[98:99], v[246:247]
	v_mov_b64_e32 v[100:101], v[248:249]
	s_waitcnt vmcnt(0)
	v_pk_fma_f32 v[218:219], v[222:223], v[98:99], v[218:219]
	v_pk_fma_f32 v[222:223], v[94:95], v[100:101], v[92:93]
	v_mul_f32_e32 v92, 0xbfb8aa3b, v91
	v_exp_f32_e32 v92, v92
	s_nop 0
	v_add_f32_e32 v92, 1.0, v92
	v_rcp_f32_e32 v225, v92
	s_nop 0
	v_pk_mul_f32 v[224:225], v[224:225], v[90:91]
	global_load_dwordx4 v[90:93], v[96:97], off offset:192
	s_nop 0
	global_load_dwordx4 v[94:97], v[104:105], off offset:192
	s_nop 0
	v_mov_b64_e32 v[102:103], v[250:251]
	v_mov_b64_e32 v[104:105], v[254:255]
	s_waitcnt vmcnt(0)
	v_pk_fma_f32 v[226:227], v[242:243], v[102:103], v[226:227]
	v_lshlrev_b32_e32 v242, 16, v191
	v_mul_f32_e32 v133, 0xbfb8aa3b, v242
	v_exp_f32_e32 v133, v133
	v_and_b32_e32 v243, 0xffff0000, v191
	v_and_b32_e32 v191, 0xffff0000, v193
	v_and_b32_e32 v193, 0xffff0000, v195
	v_add_f32_e32 v133, 1.0, v133
	v_rcp_f32_e32 v194, v133
	v_mul_f32_e32 v133, 0xbfb8aa3b, v243
	v_exp_f32_e32 v133, v133
	v_pk_add_f32 v[192:193], v[192:193], v[190:191] neg_lo:[0,1] neg_hi:[0,1]
	v_add_f32_e32 v133, 1.0, v133
	v_rcp_f32_e32 v195, v133
	v_pk_fma_f32 v[190:191], v[192:193], v[104:105], v[190:191]
	v_pk_mul_f32 v[192:193], v[194:195], v[242:243]
	v_lshlrev_b32_e32 v242, 16, v184
	v_and_b32_e32 v243, 0xffff0000, v184
	s_nop 1
	v_mfma_f32_16x16x32_bf16 v[64:67], v[64:67], v[8:11], v[242:245]
	v_mfma_f32_16x16x32_bf16 v[60:63], v[60:63], v[4:7], v[64:67]
	s_nop 7
	v_mov_b32_e32 v64, v61
	v_mov_b32_e32 v65, v62
	v_mov_b32_e32 v66, v60
	v_mov_b32_e32 v67, v63
	v_pk_add_f32 v[64:65], v[64:65], v[66:67]
	v_lshlrev_b32_e32 v66, 16, v183
	v_add_f32_e32 v64, v64, v65
	v_add_f32_e32 v184, 0, v64
	v_lshlrev_b32_e32 v64, 16, v182
	v_and_b32_e32 v65, 0xffff0000, v182
	v_and_b32_e32 v67, 0xffff0000, v183
	s_nop 1
	v_mfma_f32_16x16x32_bf16 v[44:47], v[44:47], v[8:11], v[64:67]
	v_mfma_f32_16x16x32_bf16 v[40:43], v[40:43], v[4:7], v[44:47]
	s_nop 7
	v_mov_b32_e32 v44, v41
	v_mov_b32_e32 v45, v42
	v_mov_b32_e32 v46, v40
	v_mov_b32_e32 v47, v43
	v_pk_add_f32 v[44:45], v[44:45], v[46:47]
	v_lshlrev_b32_e32 v46, 16, v181
	v_pk_add_f32 v[64:65], v[44:45], v[44:45] op_sel:[0,1] op_sel_hi:[1,0]
	v_lshlrev_b32_e32 v44, 16, v180
	v_and_b32_e32 v45, 0xffff0000, v180
	v_and_b32_e32 v47, 0xffff0000, v181
	s_nop 1
	v_mfma_f32_16x16x32_bf16 v[32:35], v[32:35], v[8:11], v[44:47]
	v_mfma_f32_16x16x32_bf16 v[28:31], v[28:31], v[4:7], v[32:35]
	s_nop 6
	v_lshlrev_b32_e32 v32, 16, v178
	v_and_b32_e32 v33, 0xffff0000, v178
	v_lshlrev_b32_e32 v34, 16, v179
	v_and_b32_e32 v35, 0xffff0000, v179
	v_add_f32_e32 v44, v28, v29
	v_add_f32_e32 v46, v30, v31
	v_mfma_f32_16x16x32_bf16 v[8:11], v[16:19], v[8:11], v[32:35]
	v_mfma_f32_16x16x32_bf16 v[4:7], v[12:15], v[4:7], v[8:11]
	s_nop 1
	v_and_b32_e32 v33, 0xffff0000, v174
	s_nop 4
	v_mov_b32_e32 v185, v4
	v_mov_b32_e32 v65, v5
	v_mov_b32_e32 v45, v6
	v_mov_b32_e32 v47, v7
	v_pk_add_f32 v[8:9], v[184:185], v[64:65]
	v_pk_add_f32 v[10:11], v[44:45], v[46:47]
	s_nop 0
	v_pk_add_f32 v[8:9], v[8:9], v[10:11]
	s_nop 0
	v_add_f32_e32 v8, v8, v9
	ds_bpermute_b32 v9, v131, v8
	s_waitcnt lgkmcnt(0)
	v_add_f32_e32 v8, v8, v9
	ds_bpermute_b32 v9, v129, v8
	s_waitcnt lgkmcnt(0)
	v_add_f32_e32 v32, v8, v9
	v_fmamk_f32 v17, v32, 0xbc800000, v61
	v_fmamk_f32 v16, v32, 0xbc800000, v60
	v_fmamk_f32 v63, v32, 0xbc800000, v63
	v_fmac_f32_e32 v62, 0xbc800000, v32
	v_pk_mul_f32 v[8:9], v[62:63], v[62:63]
	v_pk_mul_f32 v[10:11], v[16:17], v[16:17]
	v_fmamk_f32 v43, v32, 0xbc800000, v43
	v_pk_mov_b32 v[12:13], v[10:11], v[8:9] op_sel:[1,0]
	v_mov_b32_e32 v11, v9
	v_pk_add_f32 v[8:9], v[12:13], v[10:11]
	v_fmamk_f32 v13, v32, 0xbc800000, v41
	v_fmamk_f32 v12, v32, 0xbc800000, v40
	v_fmac_f32_e32 v42, 0xbc800000, v32
	v_pk_mul_f32 v[10:11], v[42:43], v[42:43]
	v_pk_mul_f32 v[14:15], v[12:13], v[12:13]
	v_pk_add_f32 v[8:9], v[8:9], v[8:9] op_sel_hi:[0,1]
	v_pk_mov_b32 v[18:19], v[14:15], v[10:11] op_sel:[1,0]
	v_mov_b32_e32 v15, v11
	v_pk_add_f32 v[10:11], v[18:19], v[14:15]
	v_fmac_f32_e32 v28, 0xbc800000, v32
	v_pk_add_f32 v[14:15], v[10:11], v[10:11] op_sel_hi:[0,1]
	v_fmamk_f32 v10, v32, 0xbc800000, v30
	v_fmamk_f32 v29, v32, 0xbc800000, v29
	v_mul_f32_e32 v8, v28, v28
	v_fmamk_f32 v11, v32, 0xbc800000, v31
	v_pk_fma_f32 v[18:19], v[28:29], v[28:29], v[8:9] op_sel_hi:[1,1,0]
	v_mul_f32_e32 v8, v10, v10
	v_pk_fma_f32 v[30:31], v[10:11], v[10:11], v[8:9] op_sel_hi:[1,1,0]
	v_fmamk_f32 v7, v32, 0xbc800000, v7
	v_fmamk_f32 v6, v32, 0xbc800000, v6
	v_fmamk_f32 v5, v32, 0xbc800000, v5
	v_fmac_f32_e32 v4, 0xbc800000, v32
	v_mul_f32_e32 v18, v4, v4
	v_mul_f32_e32 v30, v5, v5
	v_mul_f32_e32 v8, v6, v6
	v_mul_f32_e32 v14, v7, v7
	v_pk_add_f32 v[18:19], v[18:19], v[30:31]
	v_pk_add_f32 v[8:9], v[8:9], v[14:15]
	v_mov_b32_e32 v15, v70
	v_pk_add_f32 v[8:9], v[18:19], v[8:9]
	v_lshlrev_b32_e32 v32, 16, v174
	v_mov_b32_e32 v14, v8
	v_mov_b32_e32 v70, v9
	v_pk_add_f32 v[8:9], v[14:15], v[70:71]
	ds_bpermute_b32 v15, v131, v9
	ds_bpermute_b32 v14, v131, v8
	s_waitcnt lgkmcnt(0)
	v_pk_add_f32 v[8:9], v[8:9], v[14:15]
	ds_bpermute_b32 v15, v129, v9
	ds_bpermute_b32 v14, v129, v8
	s_waitcnt lgkmcnt(0)
	v_pk_add_f32 v[8:9], v[8:9], v[14:15]
	s_nop 0
	v_pk_fma_f32 v[8:9], v[8:9], s[84:85], v[156:157] op_sel_hi:[1,0,0]
	s_nop 0
	v_mul_f32_e32 v14, 0x4b800000, v9
	v_cmp_gt_f32_e64 s[4:5], s75, v9
	v_cmp_gt_f32_e32 vcc, s75, v8
	s_nop 0
	v_cndmask_b32_e64 v9, v9, v14, s[4:5]
	v_rsq_f32_e32 v9, v9
	s_nop 0
	v_mul_f32_e32 v14, 0x45800000, v9
	v_cndmask_b32_e64 v14, v9, v14, s[4:5]
	v_pk_mul_f32 v[18:19], v[188:189], v[14:15] op_sel_hi:[1,0]
	v_pk_mul_f32 v[30:31], v[38:39], v[14:15] op_sel_hi:[1,0]
	v_pk_fma_f32 v[18:19], v[20:21], v[18:19], v[24:25]
	v_pk_fma_f32 v[30:31], v[22:23], v[30:31], v[26:27]
	v_pk_fma_f32 v[18:19], v[168:169], v[198:199], v[18:19] op_sel_hi:[0,1,1]
	v_pk_fma_f32 v[30:31], v[168:169], v[202:203], v[30:31] op_sel_hi:[0,1,1]
	v_pk_mul_f32 v[18:19], v[200:201], v[18:19]
	v_pk_mul_f32 v[30:31], v[206:207], v[30:31]
	v_cvt_pk_bf16_f32 v18, v18, v19
	v_cvt_pk_bf16_f32 v19, v30, v31
	global_store_dwordx2 v[204:205], v[18:19], off offset:1536
	v_pk_mul_f32 v[18:19], v[186:187], v[14:15] op_sel_hi:[1,0]
	v_pk_mul_f32 v[30:31], v[50:51], v[14:15] op_sel_hi:[1,0]
	v_pk_fma_f32 v[18:19], v[52:53], v[18:19], v[56:57]
	v_pk_fma_f32 v[30:31], v[54:55], v[30:31], v[58:59]
	v_pk_fma_f32 v[18:19], v[168:169], v[210:211], v[18:19] op_sel_hi:[0,1,1]
	v_pk_fma_f32 v[30:31], v[168:169], v[214:215], v[30:31] op_sel_hi:[0,1,1]
	v_pk_mul_f32 v[18:19], v[212:213], v[18:19]
	v_pk_mul_f32 v[30:31], v[216:217], v[30:31]
	v_cvt_pk_bf16_f32 v18, v18, v19
	v_cvt_pk_bf16_f32 v19, v30, v31
	global_store_dwordx2 v[208:209], v[18:19], off offset:1568
	v_pk_mul_f32 v[18:19], v[68:69], v[14:15] op_sel_hi:[1,0]
	v_pk_mul_f32 v[30:31], v[48:49], v[14:15] op_sel_hi:[1,0]
	v_pk_fma_f32 v[18:19], v[78:79], v[18:19], v[82:83]
	v_pk_fma_f32 v[30:31], v[80:81], v[30:31], v[84:85]
	v_pk_fma_f32 v[18:19], v[168:169], v[218:219], v[18:19] op_sel_hi:[0,1,1]
	v_pk_fma_f32 v[30:31], v[168:169], v[222:223], v[30:31] op_sel_hi:[0,1,1]
	v_pk_mul_f32 v[18:19], v[220:221], v[18:19]
	v_pk_mul_f32 v[30:31], v[224:225], v[30:31]
	v_cvt_pk_bf16_f32 v18, v18, v19
	v_cvt_pk_bf16_f32 v19, v30, v31
	v_mul_f32_e32 v9, 0x4b800000, v8
	global_store_dwordx2 v[208:209], v[18:19], off offset:1600
	v_pk_mul_f32 v[18:19], v[72:73], v[14:15] op_sel_hi:[1,0]
	v_pk_mul_f32 v[14:15], v[36:37], v[14:15] op_sel_hi:[1,0]
	v_cndmask_b32_e32 v8, v8, v9, vcc
	v_pk_fma_f32 v[18:19], v[90:91], v[18:19], v[94:95]
	v_pk_fma_f32 v[14:15], v[92:93], v[14:15], v[96:97]
	v_rsq_f32_e32 v8, v8
	v_pk_fma_f32 v[18:19], v[168:169], v[226:227], v[18:19] op_sel_hi:[0,1,1]
	v_pk_fma_f32 v[14:15], v[168:169], v[190:191], v[14:15] op_sel_hi:[0,1,1]
	v_pk_mul_f32 v[18:19], v[228:229], v[18:19]
	v_pk_mul_f32 v[14:15], v[192:193], v[14:15]
	v_cvt_pk_bf16_f32 v18, v18, v19
	v_cvt_pk_bf16_f32 v19, v14, v15
	global_store_dwordx2 v[208:209], v[18:19], off offset:1632
	v_mul_f32_e32 v9, 0x45800000, v8
	v_lshlrev_b32_e32 v18, 16, v172
	v_cndmask_b32_e32 v8, v8, v9, vcc
	v_mul_f32_e32 v9, 0xbfb8aa3b, v18
	v_exp_f32_e32 v9, v9
	v_and_b32_e32 v19, 0xffff0000, v172
	v_lshlrev_b32_e32 v30, 16, v170
	v_and_b32_e32 v31, 0xffff0000, v170
	v_add_f32_e32 v9, 1.0, v9
	v_rcp_f32_e32 v34, v9
	v_pk_mul_f32 v[16:17], v[16:17], v[8:9] op_sel_hi:[1,0]
	v_mul_f32_e32 v9, 0xbfb8aa3b, v19
	v_exp_f32_e32 v9, v9
	v_pk_add_f32 v[32:33], v[32:33], v[30:31] neg_lo:[0,1] neg_hi:[0,1]
	v_pk_fma_f32 v[16:17], v[20:21], v[16:17], v[24:25]
	v_pk_fma_f32 v[30:31], v[32:33], v[74:75], v[30:31]
	v_add_f32_e32 v9, 1.0, v9
	v_rcp_f32_e32 v35, v9
	v_pk_fma_f32 v[16:17], v[2:3], v[30:31], v[16:17] op_sel_hi:[0,1,1]
	v_lshlrev_b32_e32 v20, 16, v171
	v_and_b32_e32 v21, 0xffff0000, v171
	v_pk_mul_f32 v[18:19], v[34:35], v[18:19]
	v_lshlrev_b32_e32 v24, 16, v175
	v_pk_mul_f32 v[16:17], v[18:19], v[16:17]
	v_lshlrev_b32_e32 v18, 16, v173
	v_mul_f32_e32 v9, 0xbfb8aa3b, v18
	v_exp_f32_e32 v9, v9
	v_and_b32_e32 v25, 0xffff0000, v175
	v_and_b32_e32 v19, 0xffff0000, v173
	v_pk_add_f32 v[24:25], v[24:25], v[20:21] neg_lo:[0,1] neg_hi:[0,1]
	v_add_f32_e32 v9, 1.0, v9
	v_rcp_f32_e32 v30, v9
	v_pk_fma_f32 v[20:21], v[24:25], v[76:77], v[20:21]
	v_pk_mul_f32 v[24:25], v[62:63], v[8:9] op_sel_hi:[1,0]
	v_mul_f32_e32 v9, 0xbfb8aa3b, v19
	v_exp_f32_e32 v9, v9
	v_pk_fma_f32 v[22:23], v[22:23], v[24:25], v[26:27]
	v_lshlrev_b64 v[14:15], 11, v[176:177]
	v_pk_fma_f32 v[20:21], v[2:3], v[20:21], v[22:23] op_sel_hi:[0,1,1]
	v_add_f32_e32 v9, 1.0, v9
	v_rcp_f32_e32 v31, v9
	v_lshl_add_u64 v[14:15], s[6:7], 0, v[14:15]
	v_cvt_pk_bf16_f32 v16, v16, v17
	v_pk_mul_f32 v[18:19], v[30:31], v[18:19]
	s_nop 0
	v_pk_mul_f32 v[18:19], v[18:19], v[20:21]
	v_lshlrev_b32_e32 v20, 16, v154
	v_cvt_pk_bf16_f32 v17, v18, v19
	v_lshl_add_u64 v[18:19], v[14:15], 0, v[148:149]
	global_store_dwordx2 v[18:19], v[16:17], off offset:1536
	v_lshlrev_b32_e32 v16, 16, v150
	v_mul_f32_e32 v9, 0xbfb8aa3b, v16
	v_exp_f32_e32 v9, v9
	v_and_b32_e32 v17, 0xffff0000, v150
	v_lshlrev_b32_e32 v18, 16, v152
	v_and_b32_e32 v19, 0xffff0000, v152
	v_add_f32_e32 v9, 1.0, v9
	v_rcp_f32_e32 v22, v9
	v_pk_mul_f32 v[12:13], v[12:13], v[8:9] op_sel_hi:[1,0]
	v_mul_f32_e32 v9, 0xbfb8aa3b, v17
	v_exp_f32_e32 v9, v9
	v_and_b32_e32 v21, 0xffff0000, v154
	v_pk_add_f32 v[20:21], v[20:21], v[18:19] neg_lo:[0,1] neg_hi:[0,1]
	v_pk_fma_f32 v[12:13], v[52:53], v[12:13], v[56:57]
	v_add_f32_e32 v9, 1.0, v9
	v_rcp_f32_e32 v23, v9
	v_pk_fma_f32 v[18:19], v[20:21], v[86:87], v[18:19]
	v_lshlrev_b32_e32 v20, 16, v155
	v_pk_fma_f32 v[12:13], v[2:3], v[18:19], v[12:13] op_sel_hi:[0,1,1]
	v_pk_mul_f32 v[16:17], v[22:23], v[16:17]
	v_lshlrev_b32_e32 v18, 16, v153
	v_pk_mul_f32 v[12:13], v[16:17], v[12:13]
	v_lshlrev_b32_e32 v16, 16, v151
	v_mul_f32_e32 v9, 0xbfb8aa3b, v16
	v_exp_f32_e32 v9, v9
	v_and_b32_e32 v19, 0xffff0000, v153
	v_and_b32_e32 v21, 0xffff0000, v155
	v_and_b32_e32 v17, 0xffff0000, v151
	v_add_f32_e32 v9, 1.0, v9
	v_pk_add_f32 v[20:21], v[20:21], v[18:19] neg_lo:[0,1] neg_hi:[0,1]
	v_rcp_f32_e32 v22, v9
	v_pk_fma_f32 v[18:19], v[20:21], v[88:89], v[18:19]
	v_pk_mul_f32 v[20:21], v[42:43], v[8:9] op_sel_hi:[1,0]
	v_mul_f32_e32 v9, 0xbfb8aa3b, v17
	v_exp_f32_e32 v9, v9
	v_pk_fma_f32 v[20:21], v[54:55], v[20:21], v[58:59]
	v_add_f32_e32 v9, 1.0, v9
	v_rcp_f32_e32 v23, v9
	v_pk_fma_f32 v[18:19], v[2:3], v[18:19], v[20:21] op_sel_hi:[0,1,1]
	v_pk_mul_f32 v[16:17], v[22:23], v[16:17]
	s_nop 0
	v_pk_mul_f32 v[16:17], v[16:17], v[18:19]
	v_cvt_pk_bf16_f32 v18, v12, v13
	v_lshl_add_u64 v[12:13], v[14:15], 0, v[196:197]
	v_lshlrev_b32_e32 v14, 16, v142
	v_mul_f32_e32 v9, 0xbfb8aa3b, v14
	v_exp_f32_e32 v9, v9
	v_cvt_pk_bf16_f32 v19, v16, v17
	global_store_dwordx2 v[12:13], v[18:19], off offset:1568
	v_lshlrev_b32_e32 v16, 16, v144
	v_and_b32_e32 v17, 0xffff0000, v144
	v_lshlrev_b32_e32 v18, 16, v146
	v_and_b32_e32 v19, 0xffff0000, v146
	v_and_b32_e32 v15, 0xffff0000, v142
	v_add_f32_e32 v9, 1.0, v9
	v_pk_add_f32 v[18:19], v[18:19], v[16:17] neg_lo:[0,1] neg_hi:[0,1]
	v_rcp_f32_e32 v20, v9
	v_pk_fma_f32 v[16:17], v[18:19], v[98:99], v[16:17]
	v_pk_mul_f32 v[18:19], v[28:29], v[8:9] op_sel_hi:[1,0]
	v_mul_f32_e32 v9, 0xbfb8aa3b, v15
	v_exp_f32_e32 v9, v9
	v_pk_fma_f32 v[18:19], v[78:79], v[18:19], v[82:83]
	v_add_f32_e32 v9, 1.0, v9
	v_rcp_f32_e32 v21, v9
	v_pk_fma_f32 v[16:17], v[2:3], v[16:17], v[18:19] op_sel_hi:[0,1,1]
	v_lshlrev_b32_e32 v18, 16, v145
	v_and_b32_e32 v19, 0xffff0000, v145
	v_pk_mul_f32 v[14:15], v[20:21], v[14:15]
	v_lshlrev_b32_e32 v20, 16, v147
	v_pk_mul_f32 v[14:15], v[14:15], v[16:17]
	v_lshlrev_b32_e32 v16, 16, v143
	v_mul_f32_e32 v9, 0xbfb8aa3b, v16
	v_exp_f32_e32 v9, v9
	v_and_b32_e32 v17, 0xffff0000, v143
	v_and_b32_e32 v21, 0xffff0000, v147
	v_pk_add_f32 v[20:21], v[20:21], v[18:19] neg_lo:[0,1] neg_hi:[0,1]
	v_add_f32_e32 v9, 1.0, v9
	v_rcp_f32_e32 v22, v9
	v_pk_mul_f32 v[10:11], v[10:11], v[8:9] op_sel_hi:[1,0]
	v_mul_f32_e32 v9, 0xbfb8aa3b, v17
	v_exp_f32_e32 v9, v9
	v_pk_fma_f32 v[18:19], v[20:21], v[100:101], v[18:19]
	v_pk_fma_f32 v[10:11], v[80:81], v[10:11], v[84:85]
	v_cvt_pk_bf16_f32 v14, v14, v15
	v_add_f32_e32 v9, 1.0, v9
	v_rcp_f32_e32 v23, v9
	v_pk_fma_f32 v[10:11], v[2:3], v[18:19], v[10:11] op_sel_hi:[0,1,1]
	v_pk_mul_f32 v[16:17], v[22:23], v[16:17]
	s_nop 0
	v_pk_mul_f32 v[10:11], v[16:17], v[10:11]
	v_lshlrev_b32_e32 v16, 16, v140
	v_cvt_pk_bf16_f32 v15, v10, v11
	v_lshlrev_b32_e32 v10, 16, v136
	v_mul_f32_e32 v9, 0xbfb8aa3b, v10
	v_exp_f32_e32 v9, v9
	v_and_b32_e32 v11, 0xffff0000, v136
	global_store_dwordx2 v[12:13], v[14:15], off offset:1600
	v_lshlrev_b32_e32 v14, 16, v138
	v_add_f32_e32 v9, 1.0, v9
	v_rcp_f32_e32 v18, v9
	v_pk_mul_f32 v[4:5], v[4:5], v[8:9] op_sel_hi:[1,0]
	v_mul_f32_e32 v9, 0xbfb8aa3b, v11
	v_exp_f32_e32 v9, v9
	v_and_b32_e32 v15, 0xffff0000, v138
	v_and_b32_e32 v17, 0xffff0000, v140
	v_pk_add_f32 v[16:17], v[16:17], v[14:15] neg_lo:[0,1] neg_hi:[0,1]
	v_add_f32_e32 v9, 1.0, v9
	v_rcp_f32_e32 v19, v9
	v_pk_fma_f32 v[14:15], v[16:17], v[102:103], v[14:15]
	v_pk_fma_f32 v[4:5], v[90:91], v[4:5], v[94:95]
	v_lshlrev_b32_e32 v16, 16, v141
	v_pk_fma_f32 v[4:5], v[2:3], v[14:15], v[4:5] op_sel_hi:[0,1,1]
	v_pk_mul_f32 v[10:11], v[18:19], v[10:11]
	v_lshlrev_b32_e32 v14, 16, v139
	v_pk_mul_f32 v[4:5], v[10:11], v[4:5]
	v_lshlrev_b32_e32 v10, 16, v137
	v_mul_f32_e32 v9, 0xbfb8aa3b, v10
	v_exp_f32_e32 v9, v9
	v_and_b32_e32 v15, 0xffff0000, v139
	v_and_b32_e32 v17, 0xffff0000, v141
	v_pk_add_f32 v[16:17], v[16:17], v[14:15] neg_lo:[0,1] neg_hi:[0,1]
	v_add_f32_e32 v9, 1.0, v9
	v_pk_mul_f32 v[6:7], v[6:7], v[8:9] op_sel_hi:[1,0]
	v_and_b32_e32 v11, 0xffff0000, v137
	v_pk_fma_f32 v[14:15], v[16:17], v[104:105], v[14:15]
	v_pk_fma_f32 v[6:7], v[92:93], v[6:7], v[96:97]
	v_rcp_f32_e32 v18, v9
	v_pk_fma_f32 v[6:7], v[2:3], v[14:15], v[6:7] op_sel_hi:[0,1,1]
	v_mul_f32_e32 v2, 0xbfb8aa3b, v11
	v_exp_f32_e32 v2, v2
	v_cvt_pk_bf16_f32 v4, v4, v5
	v_add_f32_e32 v2, 1.0, v2
	v_rcp_f32_e32 v19, v2
	s_nop 0
	v_pk_mul_f32 v[8:9], v[18:19], v[10:11]
	s_nop 0
	v_pk_mul_f32 v[6:7], v[8:9], v[6:7]
	s_nop 0
	v_cvt_pk_bf16_f32 v5, v6, v7
	global_store_dwordx2 v[12:13], v[4:5], off offset:1632
